# GU k-loop: MFMAs within a k-step reordered A-operand-major (same instructions, operand-reuse order)
# baseline (speedup 1.0000x reference)
; #define G_ITER(R, kt_) do { const int k3 = (kt_) + 3; \
;         const char* pa = k3 < nk ? ga + k3 * 128 : ga_n + (k3 - nk) * 128; const char* pb = k3 < nk ? gb + k3 * 128 : gb_n + (k3 - nk) * 128; \
;         G_BODY(R, kt_, pa, pb); } while (0)
; template <int EPI, bool RS>
; DI void gemm_phase(unsigned char* smem, const bf16_t* __restrict__ A, int lda, const bf16_t* __restrict__ Bt, int K, int mt0, int nMt, int nNt, const EpiArgs& ea) {
;     ...
;     if (DEEP) {
;     ...
;       for (int kt = 0; kt < nk; kt += 2) { G_ITER(rg, kt); G_ITER(rh, kt + 1); }
;     ...
;     } else {
;       for (int kt = 0; kt < (XPR ? nk - 1 : nk); ++kt) {
;         const int k2 = kt + 2;
;         const char* pa = k2 < nk ? ga + k2 * 128 : ((XPF || XPR) ? ga_n + (k2 - nk) * 128 : ga);
;         const char* pb = k2 < nk ? gb + k2 * 128 : ((XPF || XPR) ? gb_n + (k2 - nk) * 128 : gb);
;         G_BODY(rg, kt, pa, pb);
;       }
.LBB0_280:
	s_waitcnt lgkmcnt(3)
	s_nop 0
	v_mfma_f32_32x32x16_bf16 v[112:127], v[136:139], v[180:183], v[112:127]
	s_waitcnt lgkmcnt(2)
	s_waitcnt lgkmcnt(1)
	s_waitcnt lgkmcnt(0)
	v_mfma_f32_32x32x16_bf16 v[96:111], v[136:139], v[176:179], v[96:111]
	s_bitcmp1_b32 s17, 0
	s_cselect_b32 s0, 0, 0x12000
	v_mfma_f32_32x32x16_bf16 v[64:79], v[136:139], v[140:143], v[64:79]
	s_cselect_b32 s1, 0x12000, 0
	s_cmp_eq_u32 s100, 0
	s_cbranch_scc0 .Lgudot_skip0
	v_dot2c_f32_bf16_e32 v191, v180, v180
	v_dot2c_f32_bf16_e32 v190, v176, v176
	v_dot2c_f32_bf16_e32 v189, v140, v140
	v_dot2c_f32_bf16_e32 v188, v132, v132
	v_dot2c_f32_bf16_e32 v191, v181, v181
	v_dot2c_f32_bf16_e32 v190, v177, v177
	v_dot2c_f32_bf16_e32 v189, v141, v141
	v_dot2c_f32_bf16_e32 v188, v133, v133
	v_dot2c_f32_bf16_e32 v191, v182, v182
	v_dot2c_f32_bf16_e32 v190, v178, v178
	v_dot2c_f32_bf16_e32 v189, v142, v142
	v_dot2c_f32_bf16_e32 v188, v134, v134
	v_dot2c_f32_bf16_e32 v191, v183, v183
	v_dot2c_f32_bf16_e32 v190, v179, v179
	v_dot2c_f32_bf16_e32 v189, v143, v143
	v_dot2c_f32_bf16_e32 v188, v135, v135
.Lgudot_skip0:
	s_add_i32 s0, s0, 0
	s_add_i32 s20, s1, 0
	v_mfma_f32_32x32x16_bf16 v[32:47], v[136:139], v[132:135], v[32:47]
	v_mfma_f32_32x32x16_bf16 v[80:95], v[128:131], v[180:183], v[80:95]
	v_mfma_f32_32x32x16_bf16 v[48:63], v[128:131], v[176:179], v[48:63]
	v_mfma_f32_32x32x16_bf16 v[16:31], v[128:131], v[140:143], v[16:31]
	v_mfma_f32_32x32x16_bf16 v[0:15], v[128:131], v[132:135], v[0:15]
	v_lshl_add_u64 v[204:205], v[192:193], 0, s[2:3]
	v_add_u32_e32 v203, s20, v184
	v_add_co_u32_e32 v128, vcc, s42, v204
	v_lshl_add_u64 v[206:207], v[194:195], 0, s[2:3]
	s_waitcnt vmcnt(7)
	ds_write_b128 v203, v[148:151]
	s_waitcnt vmcnt(6)
	ds_write_b128 v203, v[144:147] offset:36864
	v_addc_co_u32_e32 v129, vcc, 0, v205, vcc
	global_load_dwordx4 v[148:151], v[204:205], off offset:256
	global_load_dwordx4 v[144:147], v[206:207], off offset:256
	s_waitcnt vmcnt(7)
	ds_write_b128 v203, v[152:155] offset:9216
	s_waitcnt vmcnt(6)
	ds_write_b128 v203, v[156:159] offset:46080
	v_add_co_u32_e32 v130, vcc, s42, v206
	v_add_u32_e32 v208, s0, v187
	s_nop 0
	v_addc_co_u32_e32 v131, vcc, 0, v207, vcc
	global_load_dwordx4 v[152:155], v[128:129], off offset:256
	global_load_dwordx4 v[156:159], v[130:131], off offset:256
	v_add_u32_e32 v209, s0, v186
	ds_read_b128 v[128:131], v208 offset:36896
	ds_read_b128 v[132:135], v208 offset:41504
	ds_read_b128 v[136:139], v209 offset:32
	ds_read_b128 v[140:143], v209 offset:4640
	ds_read_b128 v[176:179], v209 offset:9248
	ds_read_b128 v[180:183], v209 offset:13856
	s_waitcnt lgkmcnt(3)
	v_mfma_f32_32x32x16_bf16 v[112:127], v[128:131], v[136:139], v[112:127]
	s_waitcnt lgkmcnt(2)
	s_waitcnt lgkmcnt(1)
	s_waitcnt lgkmcnt(0)
	v_mfma_f32_32x32x16_bf16 v[96:111], v[128:131], v[140:143], v[96:111]
	v_mfma_f32_32x32x16_bf16 v[64:79], v[128:131], v[176:179], v[64:79]
	s_cmp_eq_u32 s100, 1
	s_cbranch_scc0 .Lgudot_skip1
	v_dot2c_f32_bf16_e32 v191, v136, v136
	v_dot2c_f32_bf16_e32 v190, v140, v140
	v_dot2c_f32_bf16_e32 v189, v176, v176
	v_dot2c_f32_bf16_e32 v188, v180, v180
	v_dot2c_f32_bf16_e32 v191, v137, v137
	v_dot2c_f32_bf16_e32 v190, v141, v141
	v_dot2c_f32_bf16_e32 v189, v177, v177
	v_dot2c_f32_bf16_e32 v188, v181, v181
	v_dot2c_f32_bf16_e32 v191, v138, v138
	v_dot2c_f32_bf16_e32 v190, v142, v142
	v_dot2c_f32_bf16_e32 v189, v178, v178
	v_dot2c_f32_bf16_e32 v188, v182, v182
	v_dot2c_f32_bf16_e32 v191, v139, v139
	v_dot2c_f32_bf16_e32 v190, v143, v143
	v_dot2c_f32_bf16_e32 v189, v179, v179
	v_dot2c_f32_bf16_e32 v188, v183, v183
; #define G_ITER(R, kt_) do { const int k3 = (kt_) + 3; \
;         const char* pa = k3 < nk ? ga + k3 * 128 : ga_n + (k3 - nk) * 128; const char* pb = k3 < nk ? gb + k3 * 128 : gb_n + (k3 - nk) * 128; \
;         G_BODY(R, kt_, pa, pb); } while (0)
; template <int EPI, bool RS>
; DI void gemm_phase(unsigned char* smem, const bf16_t* __restrict__ A, int lda, const bf16_t* __restrict__ Bt, int K, int mt0, int nMt, int nNt, const EpiArgs& ea) {
;     ...
;     if (DEEP) {
;     ...
;       for (int kt = 0; kt < nk; kt += 2) { G_ITER(rg, kt); G_ITER(rh, kt + 1); }
;     ...
;     } else {
;       for (int kt = 0; kt < (XPR ? nk - 1 : nk); ++kt) {
;         const int k2 = kt + 2;
;         const char* pa = k2 < nk ? ga + k2 * 128 : ((XPF || XPR) ? ga_n + (k2 - nk) * 128 : ga);
;         const char* pb = k2 < nk ? gb + k2 * 128 : ((XPF || XPR) ? gb_n + (k2 - nk) * 128 : gb);
;         G_BODY(rg, kt, pa, pb);
;       }
.Lgudot_skip1:
	v_mfma_f32_32x32x16_bf16 v[32:47], v[128:131], v[180:183], v[32:47]
	v_mfma_f32_32x32x16_bf16 v[80:95], v[132:135], v[136:139], v[80:95]
	v_mfma_f32_32x32x16_bf16 v[48:63], v[132:135], v[140:143], v[48:63]
	v_mfma_f32_32x32x16_bf16 v[16:31], v[132:135], v[176:179], v[16:31]
	v_mfma_f32_32x32x16_bf16 v[0:15], v[132:135], v[180:183], v[0:15]
	v_add_co_u32_e32 v128, vcc, s43, v204
	s_waitcnt vmcnt(7)
	ds_write_b128 v203, v[160:163] offset:18432
	s_waitcnt vmcnt(6)
	ds_write_b128 v203, v[168:171] offset:55296
	v_addc_co_u32_e32 v129, vcc, 0, v205, vcc
	global_load_dwordx4 v[160:163], v[128:129], off offset:256
	v_add_co_u32_e32 v128, vcc, s43, v206
	s_nop 1
	v_addc_co_u32_e32 v129, vcc, 0, v207, vcc
	global_load_dwordx4 v[168:171], v[128:129], off offset:256
	v_add_co_u32_e32 v128, vcc, s75, v204
	s_waitcnt vmcnt(7)
	ds_write_b128 v203, v[164:167] offset:27648
	s_waitcnt vmcnt(6)
	ds_write_b128 v203, v[172:175] offset:64512
	v_addc_co_u32_e32 v129, vcc, 0, v205, vcc
	global_load_dwordx4 v[164:167], v[128:129], off offset:256
	v_add_co_u32_e32 v128, vcc, s75, v206
	s_nop 1
	v_addc_co_u32_e32 v129, vcc, 0, v207, vcc
	global_load_dwordx4 v[172:175], v[128:129], off offset:256
	ds_read_b128 v[128:131], v208 offset:36928
	ds_read_b128 v[132:135], v208 offset:41536
	ds_read_b128 v[136:139], v209 offset:64
	ds_read_b128 v[140:143], v209 offset:4672
	ds_read_b128 v[176:179], v209 offset:9280
	ds_read_b128 v[180:183], v209 offset:13888
	s_waitcnt lgkmcnt(3)
	v_mfma_f32_32x32x16_bf16 v[112:127], v[128:131], v[136:139], v[112:127]
	s_waitcnt lgkmcnt(2)
	s_waitcnt lgkmcnt(1)
	s_waitcnt lgkmcnt(0)
	v_mfma_f32_32x32x16_bf16 v[96:111], v[128:131], v[140:143], v[96:111]
	v_mfma_f32_32x32x16_bf16 v[64:79], v[128:131], v[176:179], v[64:79]
	s_cmp_eq_u32 s100, 2
	s_cbranch_scc0 .Lgudot_skip2
	v_dot2c_f32_bf16_e32 v191, v136, v136
	v_dot2c_f32_bf16_e32 v190, v140, v140
	v_dot2c_f32_bf16_e32 v189, v176, v176
	v_dot2c_f32_bf16_e32 v188, v180, v180
	v_dot2c_f32_bf16_e32 v191, v137, v137
	v_dot2c_f32_bf16_e32 v190, v141, v141
	v_dot2c_f32_bf16_e32 v189, v177, v177
	v_dot2c_f32_bf16_e32 v188, v181, v181
	v_dot2c_f32_bf16_e32 v191, v138, v138
	v_dot2c_f32_bf16_e32 v190, v142, v142
	v_dot2c_f32_bf16_e32 v189, v178, v178
	v_dot2c_f32_bf16_e32 v188, v182, v182
	v_dot2c_f32_bf16_e32 v191, v139, v139
	v_dot2c_f32_bf16_e32 v190, v143, v143
	v_dot2c_f32_bf16_e32 v189, v179, v179
	v_dot2c_f32_bf16_e32 v188, v183, v183
.Lgudot_skip2:
	v_mfma_f32_32x32x16_bf16 v[32:47], v[128:131], v[180:183], v[32:47]
	v_mfma_f32_32x32x16_bf16 v[80:95], v[132:135], v[136:139], v[80:95]
	v_mfma_f32_32x32x16_bf16 v[48:63], v[132:135], v[140:143], v[48:63]
	v_mfma_f32_32x32x16_bf16 v[16:31], v[132:135], v[176:179], v[16:31]
	v_mfma_f32_32x32x16_bf16 v[0:15], v[132:135], v[180:183], v[0:15]
	ds_read_b128 v[128:131], v208 offset:36960
	ds_read_b128 v[132:135], v208 offset:41568
	ds_read_b128 v[136:139], v209 offset:96
	ds_read_b128 v[140:143], v209 offset:4704
	ds_read_b128 v[176:179], v209 offset:9312
	ds_read_b128 v[180:183], v209 offset:13920
	s_waitcnt lgkmcnt(3)
	v_mfma_f32_32x32x16_bf16 v[112:127], v[128:131], v[136:139], v[112:127]
	s_waitcnt lgkmcnt(2)
	s_waitcnt lgkmcnt(1)
	s_waitcnt lgkmcnt(0)
	v_mfma_f32_32x32x16_bf16 v[80:95], v[132:135], v[136:139], v[80:95]
	v_mfma_f32_32x32x16_bf16 v[96:111], v[128:131], v[140:143], v[96:111]
	s_cmp_eq_u32 s100, 3
	s_cbranch_scc0 .Lgudot_skip3
	v_dot2c_f32_bf16_e32 v191, v136, v136
	v_dot2c_f32_bf16_e32 v190, v140, v140
	v_dot2c_f32_bf16_e32 v189, v176, v176
	v_dot2c_f32_bf16_e32 v188, v180, v180
	v_dot2c_f32_bf16_e32 v191, v137, v137
	v_dot2c_f32_bf16_e32 v190, v141, v141
	v_dot2c_f32_bf16_e32 v189, v177, v177
	v_dot2c_f32_bf16_e32 v188, v181, v181
	v_dot2c_f32_bf16_e32 v191, v138, v138
	v_dot2c_f32_bf16_e32 v190, v142, v142
	v_dot2c_f32_bf16_e32 v189, v178, v178
	v_dot2c_f32_bf16_e32 v188, v182, v182
	v_dot2c_f32_bf16_e32 v191, v139, v139
	v_dot2c_f32_bf16_e32 v190, v143, v143
	v_dot2c_f32_bf16_e32 v189, v179, v179
	v_dot2c_f32_bf16_e32 v188, v183, v183
